# v1 + FFN-up conv weights fetched by LDS-DMA before the K loop (epilogue no longer waits for its own weight load)
# speedup vs baseline: 1.0156x; 1.0016x over previous
;     __device__ __forceinline__ void operator()(const f32x4 (&acc)[2][2][4][2], const Unit& u) const {
;     ...
;             const float* cw = P->in[24] + (size_t)layer * 3 * F2; const float* cb = P->in[25] + (size_t)layer * F2;
;             bf16_t* eb = (bf16_t*)(P->ws + WS_EB);
.LBB0_327:
	s_cmp_lg_u32 s24, 3
	s_cbranch_scc1 .Lcw_noptr
	s_load_dwordx4 s[88:91], s[80:81], 0xc0

; #define LAS __attribute__((address_space(3)))
;     __device__ __forceinline__ void operator()(const f32x4 (&acc)[2][2][4][2], const Unit& u) const {
;     ...
;             LAS unsigned char* wl = lds + LDS_CW + wid * 1024;
;             { const int a_ = lane2 >> 3, q4 = (lane2 & 7) * 4;
;               const float* src = (a_ < 6 ? cw + (a_ >> 1) * F2 : cb) + (a_ & 1) * F + (unsigned)(u.pn * 128 + wc * 32 + q4);
;               const f32x4 wv = *(const f32x4*)src;
;               *(LAS f32x4*)(wl + lane2 * 16) = wv; }
.LBB0_331:
	s_cmp_lg_u32 s24, 3
	s_cbranch_scc1 .Lcw_skip
	v_mbcnt_lo_u32_b32 v130, -1, 0
	v_mbcnt_hi_u32_b32 v130, -1, v130
	v_lshrrev_b32_e32 v129, 4, v130
	v_and_b32_e32 v128, 7, v130
	v_cmp_gt_u32_e32 vcc, 3, v129
	v_lshlrev_b32_e32 v128, 2, v128
	v_bfe_u32 v131, v130, 3, 1
	s_lshl_b32 s1, s72, 7
	s_or_b32 s1, s1, s49
	v_mul_u32_u24_e32 v131, 0xb00, v131
	v_mul_u32_u24_e32 v129, 0x1600, v129
	v_add3_u32 v128, v128, v131, s1
	v_cndmask_b32_e32 v129, 0, v129, vcc
	s_waitcnt lgkmcnt(0)
	s_mul_i32 s1, s25, 0x10800
	s_add_u32 s88, s88, s1
	s_addc_u32 s89, s89, 0
	s_mul_i32 s1, s25, 0x5800
	s_add_u32 s90, s90, s1
	s_addc_u32 s91, s91, 0
	v_add_lshl_u32 v128, v128, v129, 2
	v_mov_b32_e32 v132, s88
	v_mov_b32_e32 v133, s89
	v_mov_b32_e32 v134, s90
	v_mov_b32_e32 v135, s91
	v_mov_b32_e32 v129, 0
	v_cndmask_b32_e32 v132, v134, v132, vcc
	v_cndmask_b32_e32 v133, v135, v133, vcc
	v_readlane_b32 s3, v255, 12
	v_lshl_add_u64 v[128:129], v[132:133], 0, v[128:129]
	s_mov_b32 m0, s3
	s_nop 0
	global_load_lds_dwordx4 v[128:129], off

;     __device__ __forceinline__ void operator()(const f32x4 (&acc)[2][2][4][2], const Unit& u) const {
;     ...
;             asm volatile("s_waitcnt lgkmcnt(0)" ::: "memory");
; #pragma unroll
;             for (int ai = 0; ai < 2; ++ai) {
;                 const int rowb = u.pm * BM + ai * HALF + wr * 64, q = rowb >> 6;
;                 unsigned gq[4][4], pe[2][2][4];
; #pragma unroll
;                 for (int n = 0; n < 2; ++n) {
;                     f32x4 W[2][4];
; #pragma unroll
;                     for (int part = 0; part < 2; ++part)
; #pragma unroll
;                         for (int k = 0; k < 4; ++k) W[part][k] = *(const LAS f32x4*)(wl + (k * 2 + part) * 128 + (8 * fq + 4 * n) * 4);
; #pragma unroll
;                     for (int ep = 0; ep < 2; ++ep) {
;                         f32x2 cres[2][4];
; #pragma unroll
;                         for (int part = 0; part < 2; ++part) {
;                             const f32x2 w0 = (f32x2){W[part][0][2 * ep], W[part][0][2 * ep + 1]}, w1 = (f32x2){W[part][1][2 * ep], W[part][1][2 * ep + 1]};
;                             const f32x2 w2 = (f32x2){W[part][2][2 * ep], W[part][2][2 * ep + 1]}, bb = (f32x2){W[part][3][2 * ep], W[part][3][2 * ep + 1]};
;                             const f32x2 w0a = w0 * n0, w0b = w0 * m0, w2a = w2 * n15, w2b = w2 * m15;
;                             f32x2 X[4], R[4], L[4];
; #pragma unroll
;                             for (int m = 0; m < 4; ++m) { X[m] = (f32x2){acc[ai][part][m][n][2 * ep], acc[ai][part][m][n][2 * ep + 1]};
;                                 R[m] = (f32x2){dpp_prev(X[m].x), dpp_prev(X[m].y)}; L[m] = (f32x2){dpp_next(X[m].x), dpp_next(X[m].y)}; }
; #pragma unroll
;                             for (int m = 0; m < 4; ++m) {
;                                 f32x2 c = X[m] * w1 + bb; c = R[m] * w0a + c; c = L[m] * w2a + c;
;                                 if (m > 0) c = R[m > 0 ? m - 1 : 0] * w0b + c;
;                                 if (m < 3) c = L[m < 3 ? m + 1 : 3] * w2b + c;
;                                 cres[part][m] = c;
;                             }
;                             pe[0][part][n * 2 + ep] = cvt_pk_bf16(cres[part][0].x, cres[part][0].y);
;                             pe[1][part][n * 2 + ep] = cvt_pk_bf16(cres[part][3].x, cres[part][3].y);
;                             __builtin_amdgcn_sched_barrier(0);
.LBB0_346:
	s_and_b64 vcc, exec, s[10:11]
	s_cbranch_vccz .LBB0_373
	s_cmp_eq_u32 s24, 3
	s_mov_b64 s[8:9], -1
	s_cbranch_scc0 .LBB0_373
	v_mbcnt_lo_u32_b32 v130, -1, 0
	v_mbcnt_hi_u32_b32 v130, -1, v130
	s_load_dwordx2 s[10:11], s[6:7], 0xe0
	s_lshl_b32 s1, s72, 7
	v_ashrrev_i32_e32 v128, 1, v130
	v_readlane_b32 s3, v255, 12
	v_and_b32_e32 v162, -8, v128
	v_lshlrev_b32_e32 v128, 2, v162
	v_and_b32_e32 v184, 15, v130
	v_add_u32_e32 v185, s3, v128
	v_cmp_eq_u32_e32 vcc, 0, v184
	v_cmp_eq_u32_e64 s[8:9], 15, v184
	v_mov_b32_dpp v144, v116 row_ror:1 row_mask:0xf bank_mask:0xf bound_ctrl:1
	v_cndmask_b32_e64 v168, 0, 1.0, vcc
	v_cndmask_b32_e64 v170, 0, 1.0, s[8:9]
	v_sub_f32_e32 v172, 1.0, v168
	v_sub_f32_e32 v174, 1.0, v170
	v_mov_b32_e32 v173, v172
	v_mov_b32_dpp v145, v117 row_ror:1 row_mask:0xf bank_mask:0xf bound_ctrl:1
	v_mov_b32_dpp v186, v100 row_ror:1 row_mask:0xf bank_mask:0xf bound_ctrl:1
	v_mov_b32_dpp v187, v101 row_ror:1 row_mask:0xf bank_mask:0xf bound_ctrl:1
	v_mov_b32_dpp v194, v84 row_ror:1 row_mask:0xf bank_mask:0xf bound_ctrl:1
	v_mov_b32_dpp v195, v85 row_ror:1 row_mask:0xf bank_mask:0xf bound_ctrl:1
	v_mov_b32_e32 v175, v174
	v_mov_b32_dpp v176, v116 row_ror:15 row_mask:0xf bank_mask:0xf bound_ctrl:1
	v_mov_b32_dpp v177, v117 row_ror:15 row_mask:0xf bank_mask:0xf bound_ctrl:1
	v_mov_b32_dpp v188, v100 row_ror:15 row_mask:0xf bank_mask:0xf bound_ctrl:1
	v_mov_b32_dpp v189, v101 row_ror:15 row_mask:0xf bank_mask:0xf bound_ctrl:1
	v_mov_b32_dpp v202, v84 row_ror:15 row_mask:0xf bank_mask:0xf bound_ctrl:1
	v_mov_b32_dpp v203, v85 row_ror:15 row_mask:0xf bank_mask:0xf bound_ctrl:1
	v_mov_b32_dpp v208, v52 row_ror:1 row_mask:0xf bank_mask:0xf bound_ctrl:1
	v_mov_b32_dpp v209, v53 row_ror:1 row_mask:0xf bank_mask:0xf bound_ctrl:1
	v_mov_b32_e32 v169, v168
	v_mov_b32_e32 v171, v170
	v_mov_b32_dpp v210, v52 row_ror:15 row_mask:0xf bank_mask:0xf bound_ctrl:1
	v_mov_b32_dpp v211, v53 row_ror:15 row_mask:0xf bank_mask:0xf bound_ctrl:1
	v_cmp_ne_u32_e64 s[6:7], 0, v184
	v_cmp_ne_u32_e32 vcc, 15, v184
	s_waitcnt lgkmcnt(0)
	ds_read_b128 v[136:139], v185
	ds_read_b128 v[128:131], v185 offset:128
	ds_read_b128 v[154:157], v185 offset:256
	ds_read_b128 v[190:193], v185 offset:384
	ds_read_b128 v[140:143], v185 offset:512
	ds_read_b128 v[132:135], v185 offset:640
	ds_read_b128 v[158:161], v185 offset:768
	ds_read_b128 v[204:207], v185 offset:896
	s_waitcnt lgkmcnt(0)
	v_pk_mul_f32 v[212:213], v[172:173], v[136:137] op_sel_hi:[0,1]
	v_pk_mul_f32 v[214:215], v[174:175], v[140:141] op_sel_hi:[0,1]
	v_pk_mul_f32 v[136:137], v[168:169], v[136:137] op_sel_hi:[0,1]
	v_pk_fma_f32 v[216:217], v[116:117], v[154:155], v[158:159]
	v_pk_fma_f32 v[218:219], v[100:101], v[154:155], v[158:159]
	v_pk_fma_f32 v[220:221], v[84:85], v[154:155], v[158:159]
	v_pk_fma_f32 v[146:147], v[118:119], v[156:157], v[160:161]
	v_pk_fma_f32 v[148:149], v[102:103], v[156:157], v[160:161]
	v_pk_fma_f32 v[150:151], v[86:87], v[156:157], v[160:161]
	v_pk_fma_f32 v[152:153], v[54:55], v[156:157], v[160:161]
	v_pk_fma_f32 v[154:155], v[52:53], v[154:155], v[158:159]
	v_pk_fma_f32 v[156:157], v[212:213], v[144:145], v[216:217]
	v_pk_fma_f32 v[158:159], v[212:213], v[186:187], v[218:219]
	v_pk_fma_f32 v[160:161], v[212:213], v[194:195], v[220:221]
	v_pk_mul_f32 v[140:141], v[170:171], v[140:141] op_sel_hi:[0,1]
	v_pk_fma_f32 v[154:155], v[212:213], v[208:209], v[154:155]
	v_pk_fma_f32 v[156:157], v[214:215], v[176:177], v[156:157]
	v_pk_fma_f32 v[158:159], v[214:215], v[188:189], v[158:159]
	v_pk_fma_f32 v[160:161], v[214:215], v[202:203], v[160:161]
	v_pk_fma_f32 v[154:155], v[214:215], v[210:211], v[154:155]
	v_pk_fma_f32 v[208:209], v[140:141], v[188:189], v[156:157]
	v_pk_fma_f32 v[144:145], v[136:137], v[144:145], v[158:159]
	v_pk_fma_f32 v[156:157], v[136:137], v[186:187], v[160:161]
	v_pk_fma_f32 v[186:187], v[136:137], v[194:195], v[154:155]
	v_pk_fma_f32 v[136:137], v[140:141], v[202:203], v[144:145]
	v_pk_fma_f32 v[140:141], v[140:141], v[210:211], v[156:157]
	v_cvt_pk_bf16_f32 v189, v208, v209
	v_cvt_pk_bf16_f32 v202, v186, v187
	v_pk_mul_f32 v[144:145], v[172:173], v[128:129] op_sel_hi:[0,1]
	v_mov_b32_dpp v158, v124 row_ror:1 row_mask:0xf bank_mask:0xf bound_ctrl:1
	v_mov_b32_dpp v159, v125 row_ror:1 row_mask:0xf bank_mask:0xf bound_ctrl:1
	v_pk_fma_f32 v[218:219], v[124:125], v[190:191], v[204:205]
	v_pk_mul_f32 v[176:177], v[174:175], v[132:133] op_sel_hi:[0,1]
	v_mov_b32_dpp v156, v124 row_ror:15 row_mask:0xf bank_mask:0xf bound_ctrl:1
	v_mov_b32_dpp v157, v125 row_ror:15 row_mask:0xf bank_mask:0xf bound_ctrl:1
	v_mov_b32_dpp v160, v108 row_ror:1 row_mask:0xf bank_mask:0xf bound_ctrl:1
	v_mov_b32_dpp v161, v109 row_ror:1 row_mask:0xf bank_mask:0xf bound_ctrl:1
	v_pk_fma_f32 v[218:219], v[144:145], v[158:159], v[218:219]
	v_pk_fma_f32 v[220:221], v[108:109], v[190:191], v[204:205]
	v_mov_b32_dpp v194, v108 row_ror:15 row_mask:0xf bank_mask:0xf bound_ctrl:1
	v_mov_b32_dpp v195, v109 row_ror:15 row_mask:0xf bank_mask:0xf bound_ctrl:1
	v_pk_mul_f32 v[132:133], v[170:171], v[132:133] op_sel_hi:[0,1]
	v_pk_fma_f32 v[156:157], v[176:177], v[156:157], v[218:219]
	v_pk_fma_f32 v[220:221], v[144:145], v[160:161], v[220:221]
	v_mov_b32_dpp v210, v92 row_ror:1 row_mask:0xf bank_mask:0xf bound_ctrl:1
	v_mov_b32_dpp v211, v93 row_ror:1 row_mask:0xf bank_mask:0xf bound_ctrl:1
	v_pk_mul_f32 v[128:129], v[168:169], v[128:129] op_sel_hi:[0,1]
	v_pk_fma_f32 v[218:219], v[132:133], v[194:195], v[156:157]
	v_pk_fma_f32 v[194:195], v[176:177], v[194:195], v[220:221]
	v_pk_fma_f32 v[220:221], v[92:93], v[190:191], v[204:205]
	v_mov_b32_dpp v212, v92 row_ror:15 row_mask:0xf bank_mask:0xf bound_ctrl:1
; __device__ __forceinline__ unsigned cvt_pk_bf16(float lo, float hi) { unsigned r; asm volatile("v_cvt_pk_bf16_f32 %0, %1, %2" : "=v"(r) : "v"(lo), "v"(hi)); return r; }
; __device__ __forceinline__ float dpp_prev(float x) { return __builtin_bit_cast(float, __builtin_amdgcn_mov_dpp(__builtin_bit_cast(int, x), 0x121, 0xf, 0xf, true)); }
; __device__ __forceinline__ float dpp_next(float x) { return __builtin_bit_cast(float, __builtin_amdgcn_mov_dpp(__builtin_bit_cast(int, x), 0x12F, 0xf, 0xf, true)); }
;     __device__ __forceinline__ void operator()(const f32x4 (&acc)[2][2][4][2], const Unit& u) const {
;     ...
;                             for (int m = 0; m < 4; ++m) { X[m] = (f32x2){acc[ai][part][m][n][2 * ep], acc[ai][part][m][n][2 * ep + 1]};
;                                 R[m] = (f32x2){dpp_prev(X[m].x), dpp_prev(X[m].y)}; L[m] = (f32x2){dpp_next(X[m].x), dpp_next(X[m].y)}; }
; #pragma unroll
;                             for (int m = 0; m < 4; ++m) {
;                                 f32x2 c = X[m] * w1 + bb; c = R[m] * w0a + c; c = L[m] * w2a + c;
;                                 if (m > 0) c = R[m > 0 ? m - 1 : 0] * w0b + c;
;                                 if (m < 3) c = L[m < 3 ? m + 1 : 3] * w2b + c;
;                                 cres[part][m] = c;
;                             }
;                             pe[0][part][n * 2 + ep] = cvt_pk_bf16(cres[part][0].x, cres[part][0].y);
;                             pe[1][part][n * 2 + ep] = cvt_pk_bf16(cres[part][3].x, cres[part][3].y);
;                             __builtin_amdgcn_sched_barrier(0);
;                         }
; #pragma unroll
;                         for (int m = 0; m < 4; ++m) {
;                             const f32x2 a = cres[0][m], v = cres[1][m];
;                             const f32x2 t = (a * a) * (-0.10294324f) + (-2.3022082f), z = a * t;
;                             f32x2 d; d.x = __builtin_amdgcn_exp2f(z.x) + 1.f; d.y = __builtin_amdgcn_exp2f(z.y) + 1.f;
;                             f32x2 r; r.x = __builtin_amdgcn_rcpf(d.x); r.y = __builtin_amdgcn_rcpf(d.y);
;                             const f32x2 o = (a * v) * r;
;                             gq[m][n * 2 + ep] = cvt_pk_bf16(o.x, o.y);
;                         }
	v_mov_b32_dpp v213, v93 row_ror:15 row_mask:0xf bank_mask:0xf bound_ctrl:1
	v_pk_fma_f32 v[158:159], v[128:129], v[158:159], v[194:195]
	v_pk_fma_f32 v[220:221], v[144:145], v[210:211], v[220:221]
	v_pk_fma_f32 v[194:195], v[132:133], v[212:213], v[158:159]
	v_pk_fma_f32 v[212:213], v[176:177], v[212:213], v[220:221]
	v_mov_b32_dpp v216, v68 row_ror:15 row_mask:0xf bank_mask:0xf bound_ctrl:1
	v_mov_b32_dpp v217, v69 row_ror:15 row_mask:0xf bank_mask:0xf bound_ctrl:1
	v_pk_fma_f32 v[160:161], v[128:129], v[160:161], v[212:213]
	v_mov_b32_dpp v214, v68 row_ror:1 row_mask:0xf bank_mask:0xf bound_ctrl:1
	v_mov_b32_dpp v215, v69 row_ror:1 row_mask:0xf bank_mask:0xf bound_ctrl:1
	v_pk_fma_f32 v[212:213], v[132:133], v[216:217], v[160:161]
	v_pk_fma_f32 v[132:133], v[68:69], v[190:191], v[204:205]
	v_pk_fma_f32 v[154:155], v[126:127], v[192:193], v[206:207]
	v_pk_fma_f32 v[132:133], v[144:145], v[214:215], v[132:133]
	v_pk_fma_f32 v[156:157], v[110:111], v[192:193], v[206:207]
	v_pk_fma_f32 v[132:133], v[176:177], v[216:217], v[132:133]
	v_pk_fma_f32 v[158:159], v[94:95], v[192:193], v[206:207]
	v_pk_fma_f32 v[144:145], v[128:129], v[210:211], v[132:133]
	v_pk_fma_f32 v[160:161], v[70:71], v[192:193], v[206:207]
	v_cvt_pk_bf16_f32 v128, v218, v219
	v_cvt_pk_bf16_f32 v203, v144, v145
	s_mov_b32 s22, 0xc0135761
	v_pk_mul_f32 v[132:133], v[208:209], v[208:209]
	v_mov_b64_e32 v[176:177], s[22:23]
	v_pk_fma_f32 v[132:133], v[132:133], s[38:39], v[176:177] op_sel_hi:[1,0,0] neg_lo:[1,0,0] neg_hi:[1,0,0]
	v_pk_mul_f32 v[190:191], v[208:209], v[218:219]
	v_pk_mul_f32 v[132:133], v[208:209], v[132:133]
	v_pk_mul_f32 v[144:145], v[186:187], v[144:145]
	v_exp_f32_e32 v129, v132
	v_exp_f32_e32 v132, v133
	v_add_f32_e32 v129, 1.0, v129
	v_add_f32_e32 v133, 1.0, v132
	v_rcp_f32_e32 v132, v129
	v_rcp_f32_e32 v133, v133
	s_nop 0
	v_pk_mul_f32 v[132:133], v[132:133], v[190:191]
	v_pk_mul_f32 v[190:191], v[136:137], v[136:137]
	v_cvt_pk_bf16_f32 v132, v132, v133
	s_nop 0
	v_pk_fma_f32 v[190:191], v[190:191], s[38:39], v[176:177] op_sel_hi:[1,0,0] neg_lo:[1,0,0] neg_hi:[1,0,0]
	s_nop 0
	v_pk_mul_f32 v[190:191], v[136:137], v[190:191]
	v_pk_mul_f32 v[136:137], v[136:137], v[194:195]
	v_exp_f32_e32 v129, v190
	v_exp_f32_e32 v133, v191
	v_add_f32_e32 v129, 1.0, v129
	v_add_f32_e32 v133, 1.0, v133
	v_rcp_f32_e32 v190, v129
	v_rcp_f32_e32 v191, v133
	s_nop 0
	v_pk_mul_f32 v[136:137], v[190:191], v[136:137]
	v_pk_mul_f32 v[190:191], v[140:141], v[140:141]
	v_cvt_pk_bf16_f32 v136, v136, v137
	s_nop 0
	v_pk_fma_f32 v[190:191], v[190:191], s[38:39], v[176:177] op_sel_hi:[1,0,0] neg_lo:[1,0,0] neg_hi:[1,0,0]
	s_nop 0
	v_pk_mul_f32 v[190:191], v[140:141], v[190:191]
	v_pk_mul_f32 v[140:141], v[140:141], v[212:213]
	v_exp_f32_e32 v129, v190
	v_exp_f32_e32 v133, v191
	v_add_f32_e32 v129, 1.0, v129
	v_add_f32_e32 v133, 1.0, v133
	v_rcp_f32_e32 v190, v129
	v_rcp_f32_e32 v191, v133
	s_nop 0
	v_pk_mul_f32 v[140:141], v[190:191], v[140:141]
	v_pk_mul_f32 v[190:191], v[186:187], v[186:187]
	v_cvt_pk_bf16_f32 v140, v140, v141
	s_nop 0
	v_pk_fma_f32 v[190:191], v[190:191], s[38:39], v[176:177] op_sel_hi:[1,0,0] neg_lo:[1,0,0] neg_hi:[1,0,0]
	s_nop 0
	v_pk_mul_f32 v[190:191], v[186:187], v[190:191]
	s_nop 0
	v_exp_f32_e32 v129, v190
	v_exp_f32_e32 v133, v191
	v_add_f32_e32 v129, 1.0, v129
	v_add_f32_e32 v133, 1.0, v133
	v_rcp_f32_e32 v190, v129
	v_rcp_f32_e32 v191, v133
	s_nop 0
	v_pk_mul_f32 v[144:145], v[190:191], v[144:145]
	s_nop 0
	v_cvt_pk_bf16_f32 v144, v144, v145
	v_pk_mul_f32 v[186:187], v[172:173], v[138:139] op_sel_hi:[0,1]
	v_mov_b32_dpp v204, v102 row_ror:1 row_mask:0xf bank_mask:0xf bound_ctrl:1
	v_mov_b32_dpp v205, v103 row_ror:1 row_mask:0xf bank_mask:0xf bound_ctrl:1
	v_mov_b32_dpp v208, v86 row_ror:1 row_mask:0xf bank_mask:0xf bound_ctrl:1
	v_mov_b32_dpp v209, v87 row_ror:1 row_mask:0xf bank_mask:0xf bound_ctrl:1
	v_pk_mul_f32 v[190:191], v[174:175], v[142:143] op_sel_hi:[0,1]
	v_mov_b32_dpp v192, v118 row_ror:1 row_mask:0xf bank_mask:0xf bound_ctrl:1
	v_mov_b32_dpp v193, v119 row_ror:1 row_mask:0xf bank_mask:0xf bound_ctrl:1
	v_mov_b32_dpp v206, v102 row_ror:15 row_mask:0xf bank_mask:0xf bound_ctrl:1
	v_mov_b32_dpp v207, v103 row_ror:15 row_mask:0xf bank_mask:0xf bound_ctrl:1
	v_mov_b32_dpp v210, v86 row_ror:15 row_mask:0xf bank_mask:0xf bound_ctrl:1
	v_mov_b32_dpp v211, v87 row_ror:15 row_mask:0xf bank_mask:0xf bound_ctrl:1
	v_pk_fma_f32 v[148:149], v[186:187], v[204:205], v[148:149]
	v_pk_fma_f32 v[150:151], v[186:187], v[208:209], v[150:151]
	v_mov_b32_dpp v194, v118 row_ror:15 row_mask:0xf bank_mask:0xf bound_ctrl:1
	v_mov_b32_dpp v195, v119 row_ror:15 row_mask:0xf bank_mask:0xf bound_ctrl:1
	v_pk_mul_f32 v[138:139], v[168:169], v[138:139] op_sel_hi:[0,1]
	v_pk_fma_f32 v[146:147], v[186:187], v[192:193], v[146:147]
	v_pk_fma_f32 v[148:149], v[190:191], v[206:207], v[148:149]
	v_pk_fma_f32 v[150:151], v[190:191], v[210:211], v[150:151]
	v_mov_b32_dpp v212, v54 row_ror:1 row_mask:0xf bank_mask:0xf bound_ctrl:1
	v_mov_b32_dpp v213, v55 row_ror:1 row_mask:0xf bank_mask:0xf bound_ctrl:1
	v_mov_b32_dpp v214, v54 row_ror:15 row_mask:0xf bank_mask:0xf bound_ctrl:1
	v_mov_b32_dpp v215, v55 row_ror:15 row_mask:0xf bank_mask:0xf bound_ctrl:1
	v_pk_mul_f32 v[142:143], v[170:171], v[142:143] op_sel_hi:[0,1]
	v_pk_fma_f32 v[146:147], v[190:191], v[194:195], v[146:147]
	v_pk_fma_f32 v[148:149], v[138:139], v[192:193], v[148:149]
	v_pk_fma_f32 v[150:151], v[138:139], v[204:205], v[150:151]
	v_pk_fma_f32 v[146:147], v[142:143], v[206:207], v[146:147]
	v_pk_fma_f32 v[148:149], v[142:143], v[210:211], v[148:149]
	v_pk_fma_f32 v[142:143], v[142:143], v[214:215], v[150:151]
;     __device__ __forceinline__ void operator()(const f32x4 (&acc)[2][2][4][2], const Unit& u) const {
;     ...
;                     for (int ep = 0; ep < 2; ++ep) {
;                         f32x2 cres[2][4];
; #pragma unroll
;                         for (int part = 0; part < 2; ++part) {
;                             const f32x2 w0 = (f32x2){W[part][0][2 * ep], W[part][0][2 * ep + 1]}, w1 = (f32x2){W[part][1][2 * ep], W[part][1][2 * ep + 1]};
;                             const f32x2 w2 = (f32x2){W[part][2][2 * ep], W[part][2][2 * ep + 1]}, bb = (f32x2){W[part][3][2 * ep], W[part][3][2 * ep + 1]};
;                             const f32x2 w0a = w0 * n0, w0b = w0 * m0, w2a = w2 * n15, w2b = w2 * m15;
;                             f32x2 X[4], R[4], L[4];
; #pragma unroll
;                             for (int m = 0; m < 4; ++m) { X[m] = (f32x2){acc[ai][part][m][n][2 * ep], acc[ai][part][m][n][2 * ep + 1]};
;                                 R[m] = (f32x2){dpp_prev(X[m].x), dpp_prev(X[m].y)}; L[m] = (f32x2){dpp_next(X[m].x), dpp_next(X[m].y)}; }
; #pragma unroll
;                             for (int m = 0; m < 4; ++m) {
;                                 f32x2 c = X[m] * w1 + bb; c = R[m] * w0a + c; c = L[m] * w2a + c;
;                                 if (m > 0) c = R[m > 0 ? m - 1 : 0] * w0b + c;
;                                 if (m < 3) c = L[m < 3 ? m + 1 : 3] * w2b + c;
;                                 cres[part][m] = c;
;                             }
;                             pe[0][part][n * 2 + ep] = cvt_pk_bf16(cres[part][0].x, cres[part][0].y);
;                             pe[1][part][n * 2 + ep] = cvt_pk_bf16(cres[part][3].x, cres[part][3].y);
;                             __builtin_amdgcn_sched_barrier(0);
;                         }
; #pragma unroll
;                         for (int m = 0; m < 4; ++m) {
;                             const f32x2 a = cres[0][m], v = cres[1][m];
;                             const f32x2 t = (a * a) * (-0.10294324f) + (-2.3022082f), z = a * t;
;                             f32x2 d; d.x = __builtin_amdgcn_exp2f(z.x) + 1.f; d.y = __builtin_amdgcn_exp2f(z.y) + 1.f;
;                             f32x2 r; r.x = __builtin_amdgcn_rcpf(d.x); r.y = __builtin_amdgcn_rcpf(d.y);
;                             const f32x2 o = (a * v) * r;
;                             gq[m][n * 2 + ep] = cvt_pk_bf16(o.x, o.y);
	v_pk_fma_f32 v[150:151], v[186:187], v[212:213], v[152:153]
	v_cvt_pk_bf16_f32 v204, v146, v147
	s_nop 0
	v_pk_fma_f32 v[150:151], v[190:191], v[214:215], v[150:151]
	s_nop 0
	v_pk_fma_f32 v[138:139], v[138:139], v[208:209], v[150:151]
	s_nop 0
	v_cvt_pk_bf16_f32 v205, v138, v139
	v_pk_mul_f32 v[150:151], v[172:173], v[130:131] op_sel_hi:[0,1]
	v_mov_b32_dpp v192, v110 row_ror:1 row_mask:0xf bank_mask:0xf bound_ctrl:1
	v_mov_b32_dpp v193, v111 row_ror:1 row_mask:0xf bank_mask:0xf bound_ctrl:1
	v_mov_b32_dpp v206, v94 row_ror:1 row_mask:0xf bank_mask:0xf bound_ctrl:1
	v_mov_b32_dpp v207, v95 row_ror:1 row_mask:0xf bank_mask:0xf bound_ctrl:1
	v_pk_mul_f32 v[152:153], v[174:175], v[134:135] op_sel_hi:[0,1]
	v_mov_b32_dpp v186, v126 row_ror:1 row_mask:0xf bank_mask:0xf bound_ctrl:1
	v_mov_b32_dpp v187, v127 row_ror:1 row_mask:0xf bank_mask:0xf bound_ctrl:1
	v_mov_b32_dpp v194, v110 row_ror:15 row_mask:0xf bank_mask:0xf bound_ctrl:1
	v_mov_b32_dpp v195, v111 row_ror:15 row_mask:0xf bank_mask:0xf bound_ctrl:1
	v_mov_b32_dpp v208, v94 row_ror:15 row_mask:0xf bank_mask:0xf bound_ctrl:1
	v_mov_b32_dpp v209, v95 row_ror:15 row_mask:0xf bank_mask:0xf bound_ctrl:1
	v_mov_b32_dpp v210, v70 row_ror:1 row_mask:0xf bank_mask:0xf bound_ctrl:1
	v_mov_b32_dpp v211, v71 row_ror:1 row_mask:0xf bank_mask:0xf bound_ctrl:1
	v_pk_fma_f32 v[156:157], v[150:151], v[192:193], v[156:157]
	v_pk_fma_f32 v[158:159], v[150:151], v[206:207], v[158:159]
	v_mov_b32_dpp v190, v126 row_ror:15 row_mask:0xf bank_mask:0xf bound_ctrl:1
	v_mov_b32_dpp v191, v127 row_ror:15 row_mask:0xf bank_mask:0xf bound_ctrl:1
	v_mov_b32_dpp v212, v70 row_ror:15 row_mask:0xf bank_mask:0xf bound_ctrl:1
	v_mov_b32_dpp v213, v71 row_ror:15 row_mask:0xf bank_mask:0xf bound_ctrl:1
	v_pk_mul_f32 v[130:131], v[168:169], v[130:131] op_sel_hi:[0,1]
	v_pk_fma_f32 v[154:155], v[150:151], v[186:187], v[154:155]
	v_pk_fma_f32 v[156:157], v[152:153], v[194:195], v[156:157]
	v_pk_fma_f32 v[158:159], v[152:153], v[208:209], v[158:159]
	v_pk_fma_f32 v[150:151], v[150:151], v[210:211], v[160:161]
	v_pk_mul_f32 v[134:135], v[170:171], v[134:135] op_sel_hi:[0,1]
	v_pk_fma_f32 v[154:155], v[152:153], v[190:191], v[154:155]
	v_pk_fma_f32 v[156:157], v[130:131], v[186:187], v[156:157]
	v_pk_fma_f32 v[158:159], v[130:131], v[192:193], v[158:159]
	v_pk_fma_f32 v[150:151], v[152:153], v[212:213], v[150:151]
	v_pk_fma_f32 v[154:155], v[134:135], v[194:195], v[154:155]
	v_pk_fma_f32 v[156:157], v[134:135], v[208:209], v[156:157]
	v_pk_fma_f32 v[134:135], v[134:135], v[212:213], v[158:159]
	v_pk_fma_f32 v[130:131], v[130:131], v[206:207], v[150:151]
	v_cvt_pk_bf16_f32 v129, v154, v155
	s_nop 0
	v_cvt_pk_bf16_f32 v206, v130, v131
	v_pk_mul_f32 v[150:151], v[146:147], v[146:147]
	v_pk_mul_f32 v[152:153], v[148:149], v[148:149]
	v_pk_fma_f32 v[150:151], v[150:151], s[38:39], v[176:177] op_sel_hi:[1,0,0] neg_lo:[1,0,0] neg_hi:[1,0,0]
	v_pk_fma_f32 v[152:153], v[152:153], s[38:39], v[176:177] op_sel_hi:[1,0,0] neg_lo:[1,0,0] neg_hi:[1,0,0]
	v_pk_mul_f32 v[150:151], v[146:147], v[150:151]
	v_pk_mul_f32 v[152:153], v[148:149], v[152:153]
	v_exp_f32_e32 v133, v150
	v_exp_f32_e32 v137, v151
	v_exp_f32_e32 v141, v153
	v_pk_mul_f32 v[146:147], v[146:147], v[154:155]
	v_add_f32_e32 v133, 1.0, v133
	v_add_f32_e32 v137, 1.0, v137
	v_rcp_f32_e32 v150, v133
	v_rcp_f32_e32 v151, v137
	v_exp_f32_e32 v137, v152
	v_add_f32_e32 v141, 1.0, v141
	v_pk_mul_f32 v[148:149], v[148:149], v[156:157]
	v_pk_mul_f32 v[146:147], v[150:151], v[146:147]
	v_add_f32_e32 v137, 1.0, v137
	v_pk_mul_f32 v[150:151], v[142:143], v[142:143]
	v_cvt_pk_bf16_f32 v133, v146, v147
	v_rcp_f32_e32 v146, v137
	v_rcp_f32_e32 v147, v141
	v_pk_fma_f32 v[150:151], v[150:151], s[38:39], v[176:177] op_sel_hi:[1,0,0] neg_lo:[1,0,0] neg_hi:[1,0,0]
	v_pk_mul_f32 v[134:135], v[142:143], v[134:135]
	v_pk_mul_f32 v[150:151], v[142:143], v[150:151]
	v_pk_mul_f32 v[146:147], v[146:147], v[148:149]
	v_exp_f32_e32 v141, v150
	v_pk_mul_f32 v[148:149], v[138:139], v[138:139]
	v_exp_f32_e32 v145, v151
	v_pk_fma_f32 v[148:149], v[148:149], s[38:39], v[176:177] op_sel_hi:[1,0,0] neg_lo:[1,0,0] neg_hi:[1,0,0]
	v_add_f32_e32 v141, 1.0, v141
	v_pk_mul_f32 v[148:149], v[138:139], v[148:149]
	v_cvt_pk_bf16_f32 v137, v146, v147
	v_rcp_f32_e32 v146, v141
	v_exp_f32_e32 v141, v148
	v_exp_f32_e32 v148, v149
	v_add_f32_e32 v145, 1.0, v145
	v_rcp_f32_e32 v147, v145
	v_add_f32_e32 v141, 1.0, v141
	v_add_f32_e32 v143, 1.0, v148
	v_rcp_f32_e32 v142, v141
	v_rcp_f32_e32 v143, v143
	v_pk_mul_f32 v[130:131], v[138:139], v[130:131]
	v_pk_mul_f32 v[134:135], v[146:147], v[134:135]
	v_pk_mul_f32 v[130:131], v[142:143], v[130:131]
	v_cvt_pk_bf16_f32 v141, v134, v135
	s_nop 0
	v_cvt_pk_bf16_f32 v145, v130, v131
	ds_read_b128 v[154:157], v185 offset:16
	ds_read_b128 v[146:149], v185 offset:144
	ds_read_b128 v[190:193], v185 offset:272
	ds_read_b128 v[208:211], v185 offset:400
	ds_read_b128 v[158:161], v185 offset:528
	ds_read_b128 v[150:153], v185 offset:656
	ds_read_b128 v[212:215], v185 offset:784
	ds_read_b128 v[216:219], v185 offset:912
	s_waitcnt lgkmcnt(7)
	v_pk_mul_f32 v[130:131], v[172:173], v[154:155] op_sel_hi:[0,1]
	v_mov_b32_dpp v138, v112 row_ror:1 row_mask:0xf bank_mask:0xf bound_ctrl:1
	v_mov_b32_dpp v139, v113 row_ror:1 row_mask:0xf bank_mask:0xf bound_ctrl:1
	s_waitcnt lgkmcnt(1)
; __device__ __forceinline__ unsigned cvt_pk_bf16(float lo, float hi) { unsigned r; asm volatile("v_cvt_pk_bf16_f32 %0, %1, %2" : "=v"(r) : "v"(lo), "v"(hi)); return r; }
; __device__ __forceinline__ float dpp_prev(float x) { return __builtin_bit_cast(float, __builtin_amdgcn_mov_dpp(__builtin_bit_cast(int, x), 0x121, 0xf, 0xf, true)); }
; __device__ __forceinline__ float dpp_next(float x) { return __builtin_bit_cast(float, __builtin_amdgcn_mov_dpp(__builtin_bit_cast(int, x), 0x12F, 0xf, 0xf, true)); }
;     __device__ __forceinline__ void operator()(const f32x4 (&acc)[2][2][4][2], const Unit& u) const {
;     ...
;                     for (int ep = 0; ep < 2; ++ep) {
;                         f32x2 cres[2][4];
; #pragma unroll
;                         for (int part = 0; part < 2; ++part) {
;                             const f32x2 w0 = (f32x2){W[part][0][2 * ep], W[part][0][2 * ep + 1]}, w1 = (f32x2){W[part][1][2 * ep], W[part][1][2 * ep + 1]};
;                             const f32x2 w2 = (f32x2){W[part][2][2 * ep], W[part][2][2 * ep + 1]}, bb = (f32x2){W[part][3][2 * ep], W[part][3][2 * ep + 1]};
;                             const f32x2 w0a = w0 * n0, w0b = w0 * m0, w2a = w2 * n15, w2b = w2 * m15;
;                             f32x2 X[4], R[4], L[4];
; #pragma unroll
;                             for (int m = 0; m < 4; ++m) { X[m] = (f32x2){acc[ai][part][m][n][2 * ep], acc[ai][part][m][n][2 * ep + 1]};
;                                 R[m] = (f32x2){dpp_prev(X[m].x), dpp_prev(X[m].y)}; L[m] = (f32x2){dpp_next(X[m].x), dpp_next(X[m].y)}; }
; #pragma unroll
;                             for (int m = 0; m < 4; ++m) {
;                                 f32x2 c = X[m] * w1 + bb; c = R[m] * w0a + c; c = L[m] * w2a + c;
;                                 if (m > 0) c = R[m > 0 ? m - 1 : 0] * w0b + c;
;                                 if (m < 3) c = L[m < 3 ? m + 1 : 3] * w2b + c;
;                                 cres[part][m] = c;
;                             }
;                             pe[0][part][n * 2 + ep] = cvt_pk_bf16(cres[part][0].x, cres[part][0].y);
;                             pe[1][part][n * 2 + ep] = cvt_pk_bf16(cres[part][3].x, cres[part][3].y);
;                             __builtin_amdgcn_sched_barrier(0);
	v_pk_fma_f32 v[230:231], v[112:113], v[190:191], v[212:213]
	v_pk_mul_f32 v[134:135], v[174:175], v[158:159] op_sel_hi:[0,1]
	v_mov_b32_dpp v142, v112 row_ror:15 row_mask:0xf bank_mask:0xf bound_ctrl:1
	v_mov_b32_dpp v143, v113 row_ror:15 row_mask:0xf bank_mask:0xf bound_ctrl:1
	v_mov_b32_dpp v186, v96 row_ror:1 row_mask:0xf bank_mask:0xf bound_ctrl:1
	v_mov_b32_dpp v187, v97 row_ror:1 row_mask:0xf bank_mask:0xf bound_ctrl:1
	v_pk_fma_f32 v[230:231], v[130:131], v[138:139], v[230:231]
	v_pk_fma_f32 v[232:233], v[96:97], v[190:191], v[212:213]
	v_mov_b32_dpp v194, v96 row_ror:15 row_mask:0xf bank_mask:0xf bound_ctrl:1
	v_mov_b32_dpp v195, v97 row_ror:15 row_mask:0xf bank_mask:0xf bound_ctrl:1
	v_pk_mul_f32 v[158:159], v[170:171], v[158:159] op_sel_hi:[0,1]
	v_pk_fma_f32 v[142:143], v[134:135], v[142:143], v[230:231]
	v_pk_fma_f32 v[232:233], v[130:131], v[186:187], v[232:233]
	v_mov_b32_dpp v220, v80 row_ror:1 row_mask:0xf bank_mask:0xf bound_ctrl:1
	v_mov_b32_dpp v221, v81 row_ror:1 row_mask:0xf bank_mask:0xf bound_ctrl:1
	v_pk_mul_f32 v[154:155], v[168:169], v[154:155] op_sel_hi:[0,1]
	v_pk_fma_f32 v[142:143], v[158:159], v[194:195], v[142:143]
	v_pk_fma_f32 v[194:195], v[134:135], v[194:195], v[232:233]
	v_pk_fma_f32 v[232:233], v[80:81], v[190:191], v[212:213]
	v_mov_b32_dpp v222, v80 row_ror:15 row_mask:0xf bank_mask:0xf bound_ctrl:1
	v_mov_b32_dpp v223, v81 row_ror:15 row_mask:0xf bank_mask:0xf bound_ctrl:1
	v_pk_fma_f32 v[138:139], v[154:155], v[138:139], v[194:195]
	v_pk_fma_f32 v[232:233], v[130:131], v[220:221], v[232:233]
	v_pk_fma_f32 v[138:139], v[158:159], v[222:223], v[138:139]
	v_pk_fma_f32 v[222:223], v[134:135], v[222:223], v[232:233]
	v_mov_b32_dpp v226, v48 row_ror:15 row_mask:0xf bank_mask:0xf bound_ctrl:1
	v_mov_b32_dpp v227, v49 row_ror:15 row_mask:0xf bank_mask:0xf bound_ctrl:1
	v_pk_fma_f32 v[186:187], v[154:155], v[186:187], v[222:223]
	v_mov_b32_dpp v224, v48 row_ror:1 row_mask:0xf bank_mask:0xf bound_ctrl:1
	v_mov_b32_dpp v225, v49 row_ror:1 row_mask:0xf bank_mask:0xf bound_ctrl:1
	v_pk_fma_f32 v[186:187], v[158:159], v[226:227], v[186:187]
	v_pk_fma_f32 v[158:159], v[48:49], v[190:191], v[212:213]
	v_pk_fma_f32 v[228:229], v[114:115], v[192:193], v[214:215]
	v_pk_fma_f32 v[130:131], v[130:131], v[224:225], v[158:159]
	v_pk_fma_f32 v[230:231], v[98:99], v[192:193], v[214:215]
	v_pk_fma_f32 v[130:131], v[134:135], v[226:227], v[130:131]
	v_pk_fma_f32 v[194:195], v[82:83], v[192:193], v[214:215]
	v_pk_fma_f32 v[192:193], v[50:51], v[192:193], v[214:215]
	v_pk_fma_f32 v[190:191], v[154:155], v[220:221], v[130:131]
	v_cvt_pk_bf16_f32 v154, v142, v143
	s_nop 0
	v_cvt_pk_bf16_f32 v155, v190, v191
	v_pk_mul_f32 v[130:131], v[172:173], v[146:147] op_sel_hi:[0,1]
	v_mov_b32_dpp v158, v120 row_ror:1 row_mask:0xf bank_mask:0xf bound_ctrl:1
	v_mov_b32_dpp v159, v121 row_ror:1 row_mask:0xf bank_mask:0xf bound_ctrl:1
	s_waitcnt lgkmcnt(0)
	v_pk_fma_f32 v[236:237], v[120:121], v[208:209], v[216:217]
	v_pk_mul_f32 v[134:135], v[174:175], v[150:151] op_sel_hi:[0,1]
	v_mov_b32_dpp v212, v120 row_ror:15 row_mask:0xf bank_mask:0xf bound_ctrl:1
	v_mov_b32_dpp v213, v121 row_ror:15 row_mask:0xf bank_mask:0xf bound_ctrl:1
	v_mov_b32_dpp v214, v104 row_ror:1 row_mask:0xf bank_mask:0xf bound_ctrl:1
	v_mov_b32_dpp v215, v105 row_ror:1 row_mask:0xf bank_mask:0xf bound_ctrl:1
	v_pk_fma_f32 v[236:237], v[130:131], v[158:159], v[236:237]
	v_pk_fma_f32 v[238:239], v[104:105], v[208:209], v[216:217]
	v_mov_b32_dpp v220, v104 row_ror:15 row_mask:0xf bank_mask:0xf bound_ctrl:1
	v_mov_b32_dpp v221, v105 row_ror:15 row_mask:0xf bank_mask:0xf bound_ctrl:1
	v_pk_mul_f32 v[150:151], v[170:171], v[150:151] op_sel_hi:[0,1]
	v_pk_fma_f32 v[212:213], v[134:135], v[212:213], v[236:237]
	v_pk_fma_f32 v[238:239], v[130:131], v[214:215], v[238:239]
	v_pk_mul_f32 v[146:147], v[168:169], v[146:147] op_sel_hi:[0,1]
	v_pk_fma_f32 v[212:213], v[150:151], v[220:221], v[212:213]
	v_pk_fma_f32 v[220:221], v[134:135], v[220:221], v[238:239]
	v_mov_b32_dpp v224, v88 row_ror:15 row_mask:0xf bank_mask:0xf bound_ctrl:1
	v_mov_b32_dpp v225, v89 row_ror:15 row_mask:0xf bank_mask:0xf bound_ctrl:1
	v_pk_fma_f32 v[158:159], v[146:147], v[158:159], v[220:221]
	v_mov_b32_dpp v222, v88 row_ror:1 row_mask:0xf bank_mask:0xf bound_ctrl:1
	v_mov_b32_dpp v223, v89 row_ror:1 row_mask:0xf bank_mask:0xf bound_ctrl:1
	v_pk_fma_f32 v[220:221], v[150:151], v[224:225], v[158:159]
	v_pk_fma_f32 v[158:159], v[88:89], v[208:209], v[216:217]
	v_mov_b32_dpp v232, v60 row_ror:15 row_mask:0xf bank_mask:0xf bound_ctrl:1
	v_pk_fma_f32 v[158:159], v[130:131], v[222:223], v[158:159]
	v_mov_b32_dpp v233, v61 row_ror:15 row_mask:0xf bank_mask:0xf bound_ctrl:1
	v_pk_fma_f32 v[158:159], v[134:135], v[224:225], v[158:159]
	v_mov_b32_dpp v226, v60 row_ror:1 row_mask:0xf bank_mask:0xf bound_ctrl:1
	v_pk_fma_f32 v[158:159], v[146:147], v[214:215], v[158:159]
	v_mov_b32_dpp v227, v61 row_ror:1 row_mask:0xf bank_mask:0xf bound_ctrl:1
	v_pk_fma_f32 v[150:151], v[150:151], v[232:233], v[158:159]
	v_pk_fma_f32 v[158:159], v[60:61], v[208:209], v[216:217]
	v_pk_fma_f32 v[234:235], v[122:123], v[210:211], v[218:219]
	v_pk_fma_f32 v[130:131], v[130:131], v[226:227], v[158:159]
	v_pk_fma_f32 v[236:237], v[106:107], v[210:211], v[218:219]
	v_pk_fma_f32 v[130:131], v[134:135], v[232:233], v[130:131]
	v_pk_fma_f32 v[238:239], v[90:91], v[210:211], v[218:219]
	v_pk_fma_f32 v[146:147], v[146:147], v[222:223], v[130:131]
	v_pk_fma_f32 v[210:211], v[62:63], v[210:211], v[218:219]
	v_cvt_pk_bf16_f32 v130, v212, v213
	v_cvt_pk_bf16_f32 v158, v146, v147
	v_pk_mul_f32 v[134:135], v[142:143], v[142:143]
;     __device__ __forceinline__ void operator()(const f32x4 (&acc)[2][2][4][2], const Unit& u) const {
;     ...
;                     for (int ep = 0; ep < 2; ++ep) {
;                         f32x2 cres[2][4];
; #pragma unroll
;                         for (int part = 0; part < 2; ++part) {
;                             const f32x2 w0 = (f32x2){W[part][0][2 * ep], W[part][0][2 * ep + 1]}, w1 = (f32x2){W[part][1][2 * ep], W[part][1][2 * ep + 1]};
;                             const f32x2 w2 = (f32x2){W[part][2][2 * ep], W[part][2][2 * ep + 1]}, bb = (f32x2){W[part][3][2 * ep], W[part][3][2 * ep + 1]};
;                             const f32x2 w0a = w0 * n0, w0b = w0 * m0, w2a = w2 * n15, w2b = w2 * m15;
;                             f32x2 X[4], R[4], L[4];
; #pragma unroll
;                             for (int m = 0; m < 4; ++m) { X[m] = (f32x2){acc[ai][part][m][n][2 * ep], acc[ai][part][m][n][2 * ep + 1]};
;                                 R[m] = (f32x2){dpp_prev(X[m].x), dpp_prev(X[m].y)}; L[m] = (f32x2){dpp_next(X[m].x), dpp_next(X[m].y)}; }
; #pragma unroll
;                             for (int m = 0; m < 4; ++m) {
;                                 f32x2 c = X[m] * w1 + bb; c = R[m] * w0a + c; c = L[m] * w2a + c;
;                                 if (m > 0) c = R[m > 0 ? m - 1 : 0] * w0b + c;
;                                 if (m < 3) c = L[m < 3 ? m + 1 : 3] * w2b + c;
;                                 cres[part][m] = c;
;                             }
;                             pe[0][part][n * 2 + ep] = cvt_pk_bf16(cres[part][0].x, cres[part][0].y);
;                             pe[1][part][n * 2 + ep] = cvt_pk_bf16(cres[part][3].x, cres[part][3].y);
;                             __builtin_amdgcn_sched_barrier(0);
;                         }
; #pragma unroll
;                         for (int m = 0; m < 4; ++m) {
;                             const f32x2 a = cres[0][m], v = cres[1][m];
;                             const f32x2 t = (a * a) * (-0.10294324f) + (-2.3022082f), z = a * t;
;                             f32x2 d; d.x = __builtin_amdgcn_exp2f(z.x) + 1.f; d.y = __builtin_amdgcn_exp2f(z.y) + 1.f;
;                             f32x2 r; r.x = __builtin_amdgcn_rcpf(d.x); r.y = __builtin_amdgcn_rcpf(d.y);
;                             const f32x2 o = (a * v) * r;
;                             gq[m][n * 2 + ep] = cvt_pk_bf16(o.x, o.y);
	v_pk_mul_f32 v[208:209], v[138:139], v[138:139]
	v_pk_fma_f32 v[134:135], v[134:135], s[38:39], v[176:177] op_sel_hi:[1,0,0] neg_lo:[1,0,0] neg_hi:[1,0,0]
	v_pk_fma_f32 v[208:209], v[208:209], s[38:39], v[176:177] op_sel_hi:[1,0,0] neg_lo:[1,0,0] neg_hi:[1,0,0]
	v_pk_mul_f32 v[134:135], v[142:143], v[134:135]
	v_pk_mul_f32 v[208:209], v[138:139], v[208:209]
	v_exp_f32_e32 v131, v134
	v_exp_f32_e32 v134, v135
	v_exp_f32_e32 v159, v209
	v_pk_mul_f32 v[142:143], v[142:143], v[212:213]
	v_add_f32_e32 v131, 1.0, v131
	v_add_f32_e32 v135, 1.0, v134
	v_rcp_f32_e32 v134, v131
	v_rcp_f32_e32 v135, v135
	v_exp_f32_e32 v131, v208
	v_pk_mul_f32 v[208:209], v[186:187], v[186:187]
	v_pk_mul_f32 v[138:139], v[138:139], v[220:221]
	v_pk_mul_f32 v[134:135], v[134:135], v[142:143]
	v_pk_fma_f32 v[208:209], v[208:209], s[38:39], v[176:177] op_sel_hi:[1,0,0] neg_lo:[1,0,0] neg_hi:[1,0,0]
	v_cvt_pk_bf16_f32 v134, v134, v135
	v_add_f32_e32 v131, 1.0, v131
	v_add_f32_e32 v135, 1.0, v159
	v_pk_mul_f32 v[208:209], v[186:187], v[208:209]
	v_rcp_f32_e32 v142, v131
	v_rcp_f32_e32 v143, v135
	v_exp_f32_e32 v131, v208
	v_exp_f32_e32 v135, v209
	v_pk_mul_f32 v[208:209], v[190:191], v[190:191]
	v_pk_mul_f32 v[138:139], v[142:143], v[138:139]
	v_pk_fma_f32 v[208:209], v[208:209], s[38:39], v[176:177] op_sel_hi:[1,0,0] neg_lo:[1,0,0] neg_hi:[1,0,0]
	v_add_f32_e32 v131, 1.0, v131
	v_pk_mul_f32 v[208:209], v[190:191], v[208:209]
	v_cvt_pk_bf16_f32 v138, v138, v139
	v_rcp_f32_e32 v142, v131
	v_exp_f32_e32 v131, v208
	v_exp_f32_e32 v139, v209
	v_add_f32_e32 v135, 1.0, v135
	v_rcp_f32_e32 v143, v135
	v_add_f32_e32 v131, 1.0, v131
	v_add_f32_e32 v135, 1.0, v139
	v_pk_mul_f32 v[150:151], v[186:187], v[150:151]
	v_rcp_f32_e32 v186, v131
	v_rcp_f32_e32 v187, v135
	v_pk_mul_f32 v[146:147], v[190:191], v[146:147]
	v_pk_mul_f32 v[142:143], v[142:143], v[150:151]
	v_pk_mul_f32 v[146:147], v[186:187], v[146:147]
	v_cvt_pk_bf16_f32 v142, v142, v143
	s_nop 0
	v_cvt_pk_bf16_f32 v146, v146, v147
	v_pk_mul_f32 v[150:151], v[172:173], v[156:157] op_sel_hi:[0,1]
	v_mov_b32_dpp v190, v114 row_ror:1 row_mask:0xf bank_mask:0xf bound_ctrl:1
	v_mov_b32_dpp v191, v115 row_ror:1 row_mask:0xf bank_mask:0xf bound_ctrl:1
	v_pk_mul_f32 v[186:187], v[174:175], v[160:161] op_sel_hi:[0,1]
	v_mov_b32_dpp v208, v114 row_ror:15 row_mask:0xf bank_mask:0xf bound_ctrl:1
	v_mov_b32_dpp v209, v115 row_ror:15 row_mask:0xf bank_mask:0xf bound_ctrl:1
	v_mov_b32_dpp v212, v98 row_ror:1 row_mask:0xf bank_mask:0xf bound_ctrl:1
	v_mov_b32_dpp v213, v99 row_ror:1 row_mask:0xf bank_mask:0xf bound_ctrl:1
	v_mov_b32_dpp v216, v82 row_ror:1 row_mask:0xf bank_mask:0xf bound_ctrl:1
	v_mov_b32_dpp v217, v83 row_ror:1 row_mask:0xf bank_mask:0xf bound_ctrl:1
	v_pk_fma_f32 v[224:225], v[150:151], v[190:191], v[228:229]
	v_mov_b32_dpp v214, v98 row_ror:15 row_mask:0xf bank_mask:0xf bound_ctrl:1
	v_mov_b32_dpp v215, v99 row_ror:15 row_mask:0xf bank_mask:0xf bound_ctrl:1
	v_mov_b32_dpp v218, v82 row_ror:15 row_mask:0xf bank_mask:0xf bound_ctrl:1
	v_mov_b32_dpp v219, v83 row_ror:15 row_mask:0xf bank_mask:0xf bound_ctrl:1
	v_mov_b32_dpp v220, v50 row_ror:1 row_mask:0xf bank_mask:0xf bound_ctrl:1
	v_mov_b32_dpp v221, v51 row_ror:1 row_mask:0xf bank_mask:0xf bound_ctrl:1
	v_pk_mul_f32 v[160:161], v[170:171], v[160:161] op_sel_hi:[0,1]
	v_pk_fma_f32 v[208:209], v[186:187], v[208:209], v[224:225]
	v_pk_fma_f32 v[224:225], v[150:151], v[212:213], v[230:231]
	v_pk_fma_f32 v[194:195], v[150:151], v[216:217], v[194:195]
	v_mov_b32_dpp v222, v50 row_ror:15 row_mask:0xf bank_mask:0xf bound_ctrl:1
	v_mov_b32_dpp v223, v51 row_ror:15 row_mask:0xf bank_mask:0xf bound_ctrl:1
	v_pk_mul_f32 v[156:157], v[168:169], v[156:157] op_sel_hi:[0,1]
	v_pk_fma_f32 v[208:209], v[160:161], v[214:215], v[208:209]
	v_pk_fma_f32 v[214:215], v[186:187], v[214:215], v[224:225]
	v_pk_fma_f32 v[194:195], v[186:187], v[218:219], v[194:195]
	v_pk_fma_f32 v[150:151], v[150:151], v[220:221], v[192:193]
	v_pk_fma_f32 v[190:191], v[156:157], v[190:191], v[214:215]
	v_pk_fma_f32 v[194:195], v[156:157], v[212:213], v[194:195]
	v_pk_fma_f32 v[150:151], v[186:187], v[222:223], v[150:151]
	v_pk_fma_f32 v[190:191], v[160:161], v[218:219], v[190:191]
	v_pk_fma_f32 v[160:161], v[160:161], v[222:223], v[194:195]
	v_pk_fma_f32 v[186:187], v[156:157], v[216:217], v[150:151]
	v_cvt_pk_bf16_f32 v150, v208, v209
	s_nop 0
	v_cvt_pk_bf16_f32 v151, v186, v187
	v_pk_mul_f32 v[156:157], v[172:173], v[148:149] op_sel_hi:[0,1]
	v_mov_b32_dpp v194, v122 row_ror:1 row_mask:0xf bank_mask:0xf bound_ctrl:1
	v_mov_b32_dpp v195, v123 row_ror:1 row_mask:0xf bank_mask:0xf bound_ctrl:1
	v_pk_mul_f32 v[192:193], v[174:175], v[152:153] op_sel_hi:[0,1]
	v_mov_b32_dpp v212, v122 row_ror:15 row_mask:0xf bank_mask:0xf bound_ctrl:1
	v_mov_b32_dpp v213, v123 row_ror:15 row_mask:0xf bank_mask:0xf bound_ctrl:1
	v_mov_b32_dpp v214, v106 row_ror:1 row_mask:0xf bank_mask:0xf bound_ctrl:1
	v_mov_b32_dpp v215, v107 row_ror:1 row_mask:0xf bank_mask:0xf bound_ctrl:1
	v_pk_fma_f32 v[226:227], v[156:157], v[194:195], v[234:235]
	v_mov_b32_dpp v216, v106 row_ror:15 row_mask:0xf bank_mask:0xf bound_ctrl:1
	v_mov_b32_dpp v217, v107 row_ror:15 row_mask:0xf bank_mask:0xf bound_ctrl:1
	v_pk_mul_f32 v[152:153], v[170:171], v[152:153] op_sel_hi:[0,1]
	v_pk_fma_f32 v[212:213], v[192:193], v[212:213], v[226:227]
	v_pk_fma_f32 v[226:227], v[156:157], v[214:215], v[236:237]
	v_mov_b32_dpp v218, v90 row_ror:1 row_mask:0xf bank_mask:0xf bound_ctrl:1
	v_mov_b32_dpp v219, v91 row_ror:1 row_mask:0xf bank_mask:0xf bound_ctrl:1
	v_pk_mul_f32 v[148:149], v[168:169], v[148:149] op_sel_hi:[0,1]
; __device__ __forceinline__ unsigned cvt_pk_bf16(float lo, float hi) { unsigned r; asm volatile("v_cvt_pk_bf16_f32 %0, %1, %2" : "=v"(r) : "v"(lo), "v"(hi)); return r; }
;     __device__ __forceinline__ void operator()(const f32x4 (&acc)[2][2][4][2], const Unit& u) const {
;     ...
; #pragma unroll
;                         for (int m = 0; m < 4; ++m) {
;                             const f32x2 a = cres[0][m], v = cres[1][m];
;                             const f32x2 t = (a * a) * (-0.10294324f) + (-2.3022082f), z = a * t;
;                             f32x2 d; d.x = __builtin_amdgcn_exp2f(z.x) + 1.f; d.y = __builtin_amdgcn_exp2f(z.y) + 1.f;
;                             f32x2 r; r.x = __builtin_amdgcn_rcpf(d.x); r.y = __builtin_amdgcn_rcpf(d.y);
;                             const f32x2 o = (a * v) * r;
;                             gq[m][n * 2 + ep] = cvt_pk_bf16(o.x, o.y);
;                         }
;                         __builtin_amdgcn_sched_barrier(0);
;                     }
;                 }
;                 if (fr == 0 || fr == 15) {
;                     const bool sel = fr == 15;
;                     bf16_t* ep_ = eb + (unsigned)((((q * 2 + (sel ? 1 : 0)) * 352 + (ch0 >> 3)) * 4) * 8);
; #pragma unroll
;                     for (int part = 0; part < 2; ++part) {
;                         float rw[8];
; #pragma unroll
;                         for (int e = 0; e < 8; ++e) rw[e] = sel ? acc[ai][part][3][e >> 2][e & 3] : acc[ai][part][0][e >> 2][e & 3];
;                         *(u32x4*)(ep_ + part * 8) = pack8(rw);
;                         *(u32x4*)(ep_ + (2 + part) * 8) = (u32x4){sel ? pe[1][part][0] : pe[0][part][0], sel ? pe[1][part][1] : pe[0][part][1], sel ? pe[1][part][2] : pe[0][part][2], sel ? pe[1][part][3] : pe[0][part][3]};
;                     }
;                 }
	v_pk_fma_f32 v[212:213], v[152:153], v[216:217], v[212:213]
	v_pk_fma_f32 v[216:217], v[192:193], v[216:217], v[226:227]
	v_mov_b32_dpp v220, v90 row_ror:15 row_mask:0xf bank_mask:0xf bound_ctrl:1
	v_mov_b32_dpp v221, v91 row_ror:15 row_mask:0xf bank_mask:0xf bound_ctrl:1
	v_mov_b32_dpp v222, v62 row_ror:1 row_mask:0xf bank_mask:0xf bound_ctrl:1
	v_mov_b32_dpp v223, v63 row_ror:1 row_mask:0xf bank_mask:0xf bound_ctrl:1
	v_pk_fma_f32 v[194:195], v[148:149], v[194:195], v[216:217]
	v_pk_fma_f32 v[216:217], v[156:157], v[218:219], v[238:239]
	v_mov_b32_dpp v224, v62 row_ror:15 row_mask:0xf bank_mask:0xf bound_ctrl:1
	v_mov_b32_dpp v225, v63 row_ror:15 row_mask:0xf bank_mask:0xf bound_ctrl:1
	v_pk_fma_f32 v[216:217], v[192:193], v[220:221], v[216:217]
	v_pk_fma_f32 v[156:157], v[156:157], v[222:223], v[210:211]
	v_pk_fma_f32 v[214:215], v[148:149], v[214:215], v[216:217]
	v_pk_fma_f32 v[156:157], v[192:193], v[224:225], v[156:157]
	v_pk_fma_f32 v[194:195], v[152:153], v[220:221], v[194:195]
	v_pk_fma_f32 v[152:153], v[152:153], v[224:225], v[214:215]
	v_pk_fma_f32 v[148:149], v[148:149], v[218:219], v[156:157]
	v_cvt_pk_bf16_f32 v131, v212, v213
	s_nop 0
	v_cvt_pk_bf16_f32 v156, v148, v149
	v_pk_mul_f32 v[192:193], v[208:209], v[208:209]
	v_pk_mul_f32 v[210:211], v[190:191], v[190:191]
	v_pk_fma_f32 v[192:193], v[192:193], s[38:39], v[176:177] op_sel_hi:[1,0,0] neg_lo:[1,0,0] neg_hi:[1,0,0]
	v_pk_fma_f32 v[210:211], v[210:211], s[38:39], v[176:177] op_sel_hi:[1,0,0] neg_lo:[1,0,0] neg_hi:[1,0,0]
	v_pk_mul_f32 v[192:193], v[208:209], v[192:193]
	v_pk_mul_f32 v[210:211], v[190:191], v[210:211]
	v_exp_f32_e32 v135, v192
	v_exp_f32_e32 v139, v193
	v_exp_f32_e32 v143, v211
	v_pk_mul_f32 v[208:209], v[208:209], v[212:213]
	v_add_f32_e32 v135, 1.0, v135
	v_add_f32_e32 v139, 1.0, v139
	v_rcp_f32_e32 v192, v135
	v_rcp_f32_e32 v193, v139
	v_exp_f32_e32 v139, v210
	v_add_f32_e32 v143, 1.0, v143
	v_pk_mul_f32 v[190:191], v[190:191], v[194:195]
	v_pk_mul_f32 v[192:193], v[192:193], v[208:209]
	v_add_f32_e32 v139, 1.0, v139
	v_pk_mul_f32 v[194:195], v[160:161], v[160:161]
	v_cvt_pk_bf16_f32 v135, v192, v193
	v_rcp_f32_e32 v192, v139
	v_rcp_f32_e32 v193, v143
	v_pk_fma_f32 v[194:195], v[194:195], s[38:39], v[176:177] op_sel_hi:[1,0,0] neg_lo:[1,0,0] neg_hi:[1,0,0]
	v_pk_mul_f32 v[152:153], v[160:161], v[152:153]
	v_pk_mul_f32 v[194:195], v[160:161], v[194:195]
	v_pk_mul_f32 v[190:191], v[192:193], v[190:191]
	v_exp_f32_e32 v143, v194
	v_pk_mul_f32 v[192:193], v[186:187], v[186:187]
	v_exp_f32_e32 v147, v195
	v_pk_fma_f32 v[176:177], v[192:193], s[38:39], v[176:177] op_sel_hi:[1,0,0] neg_lo:[1,0,0] neg_hi:[1,0,0]
	v_add_f32_e32 v143, 1.0, v143
	v_pk_mul_f32 v[176:177], v[186:187], v[176:177]
	v_cvt_pk_bf16_f32 v139, v190, v191
	v_rcp_f32_e32 v190, v143
	v_exp_f32_e32 v143, v176
	v_exp_f32_e32 v157, v177
	v_add_f32_e32 v147, 1.0, v147
	v_rcp_f32_e32 v191, v147
	v_add_f32_e32 v143, 1.0, v143
	v_add_f32_e32 v147, 1.0, v157
	v_rcp_f32_e32 v160, v143
	v_rcp_f32_e32 v161, v147
	v_pk_mul_f32 v[148:149], v[186:187], v[148:149]
	v_pk_mul_f32 v[152:153], v[190:191], v[152:153]
	v_pk_mul_f32 v[148:149], v[160:161], v[148:149]
	v_cvt_pk_bf16_f32 v143, v152, v153
	s_nop 0
	v_cvt_pk_bf16_f32 v147, v148, v149
	s_add_u32 s22, s10, 0x18660000
	s_addc_u32 s23, s11, 0
	v_cmp_gt_i32_e64 s[10:11], 15, v184
	s_mov_b64 s[56:57], -1
	s_and_saveexec_b64 s[58:59], s[10:11]
	v_cmp_eq_u32_e64 s[10:11], 0, v184
	s_orn2_b64 s[56:57], s[10:11], exec
	s_or_b64 exec, exec, s[58:59]
	s_or_b32 s1, s1, s49
	v_add_u32_e32 v186, s1, v162
	s_lshl_b32 s1, s73, 8
	s_add_i32 s1, s1, s33
	v_cndmask_b32_e64 v188, 0, 1, s[8:9]
	v_ashrrev_i32_e32 v187, 3, v186
	s_and_saveexec_b64 s[10:11], s[56:57]
	s_cbranch_execz .LBB0_358
	s_lshr_b32 s3, s1, 5
	v_or_b32_e32 v148, s3, v188
	v_mul_lo_u32 v148, v148, s77
	v_add_lshl_u32 v162, v148, v187, 5
	v_cndmask_b32_e64 v192, v113, v49, s[8:9]
	v_lshl_add_u64 v[152:153], v[162:163], 1, s[22:23]
	v_cndmask_b32_e64 v157, v118, v54, s[8:9]
	v_cndmask_b32_e64 v159, v119, v55, s[8:9]
	v_cndmask_b32_e64 v160, v116, v52, s[8:9]
	v_cndmask_b32_e64 v161, v117, v53, s[8:9]
	v_cndmask_b32_e64 v162, v114, v50, s[8:9]
	v_cndmask_b32_e64 v176, v115, v51, s[8:9]
	v_cndmask_b32_e64 v177, v112, v48, s[8:9]
	v_cndmask_b32_e64 v151, v150, v151, s[8:9]
	v_cndmask_b32_e64 v150, v154, v155, s[8:9]
	v_cndmask_b32_e64 v149, v204, v205, s[8:9]
	v_cndmask_b32_e64 v148, v189, v202, s[8:9]
	v_cvt_pk_bf16_f32 v190, v160, v161
	v_cvt_pk_bf16_f32 v191, v157, v159
	v_cvt_pk_bf16_f32 v192, v177, v192
	v_cvt_pk_bf16_f32 v193, v162, v176
	global_store_dwordx4 v[152:153], v[190:193], off
	global_store_dwordx4 v[152:153], v[148:151], off offset:32
	s_nop 1
	v_mov_b64_e32 v[150:151], v[122:123]
	v_mov_b64_e32 v[148:149], v[120:121]
	s_and_saveexec_b64 s[56:57], s[8:9]
	v_mov_b64_e32 v[150:151], v[62:63]
	v_mov_b32_e32 v131, v156
	v_mov_b32_e32 v130, v158
	v_mov_b32_e32 v129, v206
	v_mov_b32_e32 v128, v203
	v_mov_b64_e32 v[148:149], v[60:61]
	s_or_b64 exec, exec, s[56:57]
	v_cndmask_b32_e64 v149, v126, v70, s[8:9]
	v_cndmask_b32_e64 v150, v127, v71, s[8:9]
	v_cndmask_b32_e64 v148, v124, v68, s[8:9]
	v_cndmask_b32_e64 v154, v125, v69, s[8:9]
	v_cndmask_b32_e64 v155, v122, v62, s[8:9]
	v_cndmask_b32_e64 v156, v120, v60, s[8:9]
	v_cndmask_b32_e64 v157, v121, v61, s[8:9]
	v_cvt_pk_bf16_f32 v148, v148, v154
	v_cvt_pk_bf16_f32 v149, v149, v150
	v_cvt_pk_bf16_f32 v150, v156, v157
	v_cvt_pk_bf16_f32 v151, v155, v151
	global_store_dwordx4 v[152:153], v[148:151], off offset:16
	global_store_dwordx4 v[152:153], v[128:131], off offset:48
